# v31 + P5 sample-row out-proj units also use XCD-contiguous ids (the 4 row-groups sharing a weight column block sit on one XCD)
# speedup vs baseline: 1.0268x; 1.0030x over previous
; #define LAS __attribute__((address_space(3)))
; #define SK_LOAD(buf, c) do { _Pragma("unroll") for (int nt = 0; nt < 2; ++nt) fb[buf][nt] = *(const bf16x8*)(pb + nt * rs + 32 * (c)); \
;         _Pragma("unroll") for (int mt = 0; mt < NMT; ++mt) fa[buf][mt] = *(const bf16x8*)(pa + mt * rs + 32 * (c)); } while (0)
; #define SK_MMA(buf) do { _Pragma("unroll") for (int mt = 0; mt < NMT; ++mt) _Pragma("unroll") for (int nt = 0; nt < 2; ++nt) \
;         acc[mt][nt] = __builtin_amdgcn_mfma_f32_16x16x32_bf16(fa[buf][mt], fb[buf][nt], acc[mt][nt], 0, 0, 0); } while (0)
; template <int MT, class Epi>
; DI void skinny_unit(LAS unsigned char* lds, const bf16_t* A, const bf16_t* Wt, int K, int cgi, int k0, int row0, const Epi& E, int tid) {
;     const int lane = tid & 63, wid = tid >> 6, fr = lane & 15, fq = lane >> 4;
;     const int c0 = cgi * 32;
;     constexpr int NMT = 2 * MT;
;     const bf16_t* pa = A + (size_t)(row0 + fr) * K + k0 + wid * 256 + 8 * fq;
;     const bf16_t* pb = Wt + (size_t)(c0 + fr) * K + k0 + wid * 256 + 8 * fq;
;     const size_t rs = (size_t)16 * K;
;     f32x4 acc[NMT][2];
; #pragma unroll
;     for (int i = 0; i < NMT; ++i) { acc[i][0] = (f32x4){0.f, 0.f, 0.f, 0.f}; acc[i][1] = (f32x4){0.f, 0.f, 0.f, 0.f}; }
;     bf16x8 fb[3][2], fa[3][NMT];
;     ...
;     SK_LOAD(0, 0); SK_LOAD(1, 1);
;     SK_LOAD(2, 2); SK_MMA(0);
;     SK_LOAD(0, 3); SK_MMA(1);
;     SK_LOAD(1, 4); SK_MMA(2);
;     SK_LOAD(2, 5); SK_MMA(0);
;     SK_LOAD(0, 6); SK_MMA(1);
;     SK_LOAD(1, 7); SK_MMA(2);
;     SK_MMA(0); SK_MMA(1);
;     ...
;     constexpr int NR = 32 * MT;
;     LAS float* red = (LAS float*)lds;
; #pragma unroll
;     for (int mt = 0; mt < NMT; ++mt)
; #pragma unroll
;         for (int nt = 0; nt < 2; ++nt)
; #pragma unroll
;             for (int j = 0; j < 4; ++j) red[(wid * NR + mt * 16 + 4 * fq + j) * 32 + nt * 16 + fr] = acc[mt][nt][j];
; __global__ void __launch_bounds__(512, 2) fwd_kernel(Args a) {
;     ...
;         const SkOut SE{x_s, out + O_Y + (size_t)LP * DM, XG + (size_t)LP * DM};
;         for (int u = bx; u < 4 * (DM / 32); u += G) skinny_unit<1>(lds, MIX + (size_t)LP * DM, WOUT, DM, u >> 2, 0, (u & 3) * 32, SE, tid);
.LBB0_549:
	s_waitcnt lgkmcnt(0)
	s_mov_b64 exec, -1
	v_readlane_b32 s16, v254, 15
	v_readlane_b32 s17, v254, 16
	v_readlane_b32 s18, v254, 17
	v_readlane_b32 s19, v254, 18
	v_readlane_b32 s20, v254, 19
	v_readlane_b32 s21, v254, 20
	v_readlane_b32 s22, v254, 21
	v_readlane_b32 s23, v254, 22
	v_and_b32_e32 v20, 15, v253
	v_bfe_u32 v21, v253, 4, 2
	v_lshrrev_b32_e32 v22, 6, v253
	v_lshlrev_b32_e32 v16, 12, v20
	v_lshl_add_u32 v16, v22, 9, v16
	v_lshl_add_u32 v16, v21, 4, v16
	v_readfirstlane_b32 s1, v22
	v_lshlrev_b32_e32 v17, 12, v22
	v_lshl_add_u32 v17, v21, 9, v17
	v_lshl_add_u32 v17, v20, 2, v17
	v_lshrrev_b32_e32 v23, 3, v253
	v_and_b32_e32 v24, 7, v253
	v_lshlrev_b32_e32 v18, 7, v23
	v_lshl_add_u32 v18, v24, 4, v18
	v_lshlrev_b32_e32 v19, 13, v23
	v_lshl_add_u32 v19, v24, 4, v19
	v_lshrrev_b32_e32 v148, 4, v23
	v_lshlrev_b32_e32 v148, 10, v148
	v_lshrrev_b32_e32 v149, 1, v24
	v_lshl_add_u32 v148, v149, 8, v148
	v_and_b32_e32 v149, 15, v23
	v_lshl_add_u32 v148, v149, 4, v148
	v_and_b32_e32 v149, 1, v24
	v_lshl_add_u32 v148, v149, 3, v148
	s_add_u32 s4, s60, 0xa000000
	s_addc_u32 s5, s61, 0
	s_add_u32 s8, s60, 0x1700000
	s_addc_u32 s9, s61, 0
	s_and_b32 s98, s92, 7
	s_lshl_b32 s98, s98, 5
	s_lshr_b32 s99, s92, 3
	s_or_b32 s0, s98, s99
